# attention A: K-fragment reads issued before the tile DMA, first V-fragment reads in the wait states behind the last QK MFMA
# baseline (speedup 1.0000x reference)
.LBB0_344:
	v_fma_f32 v96, v96, s43, -v151
	v_exp_f32_e32 v96, v96
	v_fma_f32 v97, v97, s43, -v151
	v_exp_f32_e32 v97, v97
	v_fma_f32 v98, v98, s43, -v151
	v_exp_f32_e32 v98, v98
	v_fma_f32 v99, v99, s43, -v151
	v_exp_f32_e32 v99, v99
	v_fma_f32 v100, v100, s43, -v151
	v_exp_f32_e32 v100, v100
	v_fma_f32 v101, v101, s43, -v151
	v_exp_f32_e32 v101, v101
	v_fma_f32 v102, v102, s43, -v151
	v_exp_f32_e32 v102, v102
	v_fma_f32 v103, v103, s43, -v151
	v_exp_f32_e32 v103, v103
	v_add_f32_e32 v0, v96, v97
	v_add_f32_e32 v14, v98, v99
	v_cvt_pk_bf16_f32 v96, v96, v97
	v_cvt_pk_bf16_f32 v97, v98, v99
	v_cvt_pk_bf16_f32 v98, v100, v101
	v_cvt_pk_bf16_f32 v99, v102, v103
	v_add_f32_e32 v15, v100, v101
	v_add_f32_e32 v0, v0, v102
	v_add_f32_e32 v14, v14, v103
	s_waitcnt lgkmcnt(6)
	v_mfma_f32_32x32x16_bf16 v[64:79], v[2:5], v[96:99], v[64:79]
	ds_read_b64_tr_b16 v[156:157], v248 offset:12288
	ds_read_b64_tr_b16 v[158:159], v248 offset:14336
	ds_read_b64_tr_b16 v[160:161], v249 offset:12288
	ds_read_b64_tr_b16 v[162:163], v249 offset:14336
	ds_read_b64_tr_b16 v[252:253], v250 offset:12288
	ds_read_b64_tr_b16 v[254:255], v250 offset:14336
	ds_read_b64_tr_b16 v[100:101], v251 offset:12288
	ds_read_b64_tr_b16 v[102:103], v251 offset:14336
	v_fma_f32 v104, v104, s43, -v151
	v_exp_f32_e32 v104, v104
	v_fma_f32 v105, v105, s43, -v151
	v_exp_f32_e32 v105, v105
	s_waitcnt lgkmcnt(12)
	v_mfma_f32_32x32x16_bf16 v[48:63], v[6:9], v[96:99], v[48:63]
	v_fma_f32 v106, v106, s43, -v151
	v_exp_f32_e32 v106, v106
	v_fma_f32 v107, v107, s43, -v151
	v_exp_f32_e32 v107, v107
	s_waitcnt lgkmcnt(10)
	v_mfma_f32_32x32x16_bf16 v[32:47], v[10:13], v[96:99], v[32:47]
	v_fma_f32 v108, v108, s43, -v151
	v_exp_f32_e32 v108, v108
	v_fma_f32 v109, v109, s43, -v151
	v_exp_f32_e32 v109, v109
	s_waitcnt lgkmcnt(8)
	v_mfma_f32_32x32x16_bf16 v[16:31], v[244:247], v[96:99], v[16:31]
	v_fma_f32 v110, v110, s43, -v151
	v_exp_f32_e32 v110, v110
	v_fma_f32 v111, v111, s43, -v151
	v_exp_f32_e32 v111, v111
	v_add_f32_e32 v0, v0, v104
	v_add_f32_e32 v14, v14, v105
	v_add_f32_e32 v15, v15, v106
	v_add_f32_e32 v0, v0, v107
	v_cvt_pk_bf16_f32 v104, v104, v105
	v_cvt_pk_bf16_f32 v105, v106, v107
	v_cvt_pk_bf16_f32 v106, v108, v109
	v_cvt_pk_bf16_f32 v107, v110, v111
	v_add_f32_e32 v14, v14, v108
	v_add_f32_e32 v15, v15, v109
	v_add_f32_e32 v0, v0, v110
	v_add_f32_e32 v14, v14, v111
	s_waitcnt lgkmcnt(6)
	v_mfma_f32_32x32x16_bf16 v[64:79], v[156:159], v[104:107], v[64:79]
	ds_read_b64_tr_b16 v[2:3], v248 offset:16384
	ds_read_b64_tr_b16 v[4:5], v248 offset:18432
	ds_read_b64_tr_b16 v[6:7], v249 offset:16384
	ds_read_b64_tr_b16 v[8:9], v249 offset:18432
	ds_read_b64_tr_b16 v[10:11], v250 offset:16384
	ds_read_b64_tr_b16 v[12:13], v250 offset:18432
	ds_read_b64_tr_b16 v[244:245], v251 offset:16384
	ds_read_b64_tr_b16 v[246:247], v251 offset:18432
	v_fma_f32 v80, v80, s43, -v151
	v_exp_f32_e32 v80, v80
	v_fma_f32 v81, v81, s43, -v151
	v_exp_f32_e32 v81, v81
	s_waitcnt lgkmcnt(12)
	v_mfma_f32_32x32x16_bf16 v[48:63], v[160:163], v[104:107], v[48:63]
	v_fma_f32 v82, v82, s43, -v151
	v_exp_f32_e32 v82, v82
	v_fma_f32 v83, v83, s43, -v151
	v_exp_f32_e32 v83, v83
	s_waitcnt lgkmcnt(10)
	v_mfma_f32_32x32x16_bf16 v[32:47], v[252:255], v[104:107], v[32:47]
	v_fma_f32 v84, v84, s43, -v151
	v_exp_f32_e32 v84, v84
	v_fma_f32 v85, v85, s43, -v151
	v_exp_f32_e32 v85, v85
	s_waitcnt lgkmcnt(8)
	v_mfma_f32_32x32x16_bf16 v[16:31], v[100:103], v[104:107], v[16:31]
	v_fma_f32 v86, v86, s43, -v151
	v_exp_f32_e32 v86, v86
	v_fma_f32 v87, v87, s43, -v151
	v_exp_f32_e32 v87, v87
	v_add_f32_e32 v0, v0, v80
	v_add_f32_e32 v14, v14, v81
	v_add_f32_e32 v15, v15, v82
	v_add_f32_e32 v0, v0, v83
	v_cvt_pk_bf16_f32 v80, v80, v81
	v_cvt_pk_bf16_f32 v81, v82, v83
	v_cvt_pk_bf16_f32 v82, v84, v85
	v_cvt_pk_bf16_f32 v83, v86, v87
	v_add_f32_e32 v14, v14, v84
	v_add_f32_e32 v15, v15, v85
	v_add_f32_e32 v0, v0, v86
	v_add_f32_e32 v14, v14, v87
	s_waitcnt lgkmcnt(6)
	v_mfma_f32_32x32x16_bf16 v[64:79], v[2:5], v[80:83], v[64:79]
	ds_read_b64_tr_b16 v[156:157], v248 offset:20480
	ds_read_b64_tr_b16 v[158:159], v248 offset:22528
	ds_read_b64_tr_b16 v[160:161], v249 offset:20480
	ds_read_b64_tr_b16 v[162:163], v249 offset:22528
	ds_read_b64_tr_b16 v[252:253], v250 offset:20480
	ds_read_b64_tr_b16 v[254:255], v250 offset:22528
	ds_read_b64_tr_b16 v[100:101], v251 offset:20480
	ds_read_b64_tr_b16 v[102:103], v251 offset:22528
	v_fma_f32 v88, v88, s43, -v151
	v_exp_f32_e32 v88, v88
	v_fma_f32 v89, v89, s43, -v151
	v_exp_f32_e32 v89, v89
	s_waitcnt lgkmcnt(12)
	v_mfma_f32_32x32x16_bf16 v[48:63], v[6:9], v[80:83], v[48:63]
	v_fma_f32 v90, v90, s43, -v151
	v_exp_f32_e32 v90, v90
	v_fma_f32 v91, v91, s43, -v151
	v_exp_f32_e32 v91, v91
	s_waitcnt lgkmcnt(10)
	v_mfma_f32_32x32x16_bf16 v[32:47], v[10:13], v[80:83], v[32:47]
	v_fma_f32 v92, v92, s43, -v151
	v_exp_f32_e32 v92, v92
	v_fma_f32 v93, v93, s43, -v151
	v_exp_f32_e32 v93, v93
	s_waitcnt lgkmcnt(8)
	v_mfma_f32_32x32x16_bf16 v[16:31], v[244:247], v[80:83], v[16:31]
	v_fma_f32 v94, v94, s43, -v151
	v_exp_f32_e32 v94, v94
	v_fma_f32 v95, v95, s43, -v151
	v_exp_f32_e32 v95, v95
	v_add_f32_e32 v0, v0, v88
	v_add_f32_e32 v14, v14, v89
	v_add_f32_e32 v15, v15, v90
	v_add_f32_e32 v0, v0, v91
	v_cvt_pk_bf16_f32 v88, v88, v89
	v_cvt_pk_bf16_f32 v89, v90, v91
	v_cvt_pk_bf16_f32 v90, v92, v93
	v_cvt_pk_bf16_f32 v91, v94, v95
	v_add_f32_e32 v14, v14, v92
	v_add_f32_e32 v15, v15, v93
	v_add_f32_e32 v0, v0, v94
	v_add_f32_e32 v14, v14, v95
	s_waitcnt lgkmcnt(6)
	v_mfma_f32_32x32x16_bf16 v[64:79], v[156:159], v[88:91], v[64:79]
	s_waitcnt lgkmcnt(4)
	v_mfma_f32_32x32x16_bf16 v[48:63], v[160:163], v[88:91], v[48:63]
	s_waitcnt lgkmcnt(2)
	v_mfma_f32_32x32x16_bf16 v[32:47], v[252:255], v[88:91], v[32:47]
	s_waitcnt lgkmcnt(0)
	v_mfma_f32_32x32x16_bf16 v[16:31], v[100:103], v[88:91], v[16:31]
	v_add_f32_e32 v0, v0, v14
	v_add_f32_e32 v150, v150, v15
	v_add_f32_e32 v150, v150, v0

.LBB0_353:
	s_waitcnt lgkmcnt(0)
	s_barrier
	s_cmp_gt_i32 s63, s52
	s_cbranch_scc1 .Lc1_dmaonly
	s_and_b32 s38, s63, 3
	s_mulk_i32 s38, 0x6000
	s_add_i32 s38, s38, 0
	v_add_u32_e32 v0, s38, v174
	v_add_u32_e32 v14, v0, v173
	v_add_u32_e32 v15, v0, v177
	ds_read_b128 v[2:5], v14
	ds_read_b128 v[6:9], v14 offset:4096
	ds_read_b128 v[10:13], v15
	ds_read_b128 v[152:155], v15 offset:4096
	v_add_u32_e32 v14, v0, v179
	v_add_u32_e32 v15, v0, v180
	ds_read_b128 v[156:159], v14
	ds_read_b128 v[160:163], v14 offset:4096
	ds_read_b128 v[244:247], v15
	ds_read_b128 v[248:251], v15 offset:4096
	s_add_i32 s101, s63, 3
	s_cmp_ge_i32 s101, s53
	s_cbranch_scc1 .Lc1_go
	s_and_b32 s101, s101, 3
	s_mulk_i32 s101, 0x6000
	s_add_i32 s101, s101, 0
	v_lshl_add_u64 v[14:15], s[24:25], 0, v[148:149]
	s_add_i32 m0, s101, s59
	s_add_i32 s101, s101, s60
	global_load_lds_dwordx4 v[14:15], off
	s_add_i32 m0, s101, 0x2000
	v_lshl_add_u64 v[14:15], s[24:25], 0, v[130:131]
	global_load_lds_dwordx4 v[14:15], off
	v_lshl_add_u64 v[14:15], s[24:25], 0, v[146:147]
	s_add_i32 m0, s101, 0x2400
	s_nop 0
	global_load_lds_dwordx4 v[14:15], off
.Lc1_go:
	s_waitcnt lgkmcnt(6)
	v_mfma_f32_32x32x16_bf16 v[96:111], v[2:5], v[112:115], 0
	v_mfma_f32_32x32x16_bf16 v[80:95], v[6:9], v[112:115], 0
	s_waitcnt lgkmcnt(4)
	v_mfma_f32_32x32x16_bf16 v[96:111], v[10:13], v[116:119], v[96:111]
	v_mfma_f32_32x32x16_bf16 v[80:95], v[152:155], v[116:119], v[80:95]
	s_waitcnt lgkmcnt(2)
	v_mfma_f32_32x32x16_bf16 v[96:111], v[156:159], v[120:123], v[96:111]
	v_mfma_f32_32x32x16_bf16 v[80:95], v[160:163], v[120:123], v[80:95]
	s_waitcnt lgkmcnt(0)
	v_mfma_f32_32x32x16_bf16 v[80:95], v[248:251], v[124:127], v[80:95]
	v_mfma_f32_32x32x16_bf16 v[96:111], v[244:247], v[124:127], v[96:111]
	v_add3_u32 v14, s38, v185, v186
	v_add3_u32 v14, v14, v175, v176
	v_add_u32_e32 v248, v14, v187
	v_add_u32_e32 v249, v14, v190
	v_add_u32_e32 v250, v14, v191
	v_add_u32_e32 v251, v14, v192
	ds_read_b64_tr_b16 v[2:3], v248 offset:8192
	ds_read_b64_tr_b16 v[4:5], v248 offset:10240
	ds_read_b64_tr_b16 v[6:7], v249 offset:8192
	ds_read_b64_tr_b16 v[8:9], v249 offset:10240
	ds_read_b64_tr_b16 v[10:11], v250 offset:8192
	ds_read_b64_tr_b16 v[12:13], v250 offset:10240
	ds_read_b64_tr_b16 v[244:245], v251 offset:8192
	ds_read_b64_tr_b16 v[246:247], v251 offset:10240
	v_max3_f32 v0, v80, v81, v82
	v_max3_f32 v14, v83, v84, v85
	v_max3_f32 v15, v86, v87, v88
	v_max3_f32 v153, v89, v90, v91
	v_max3_f32 v0, v0, v92, v93
	v_max3_f32 v14, v14, v94, v95
	v_max3_f32 v15, v15, v96, v97
	v_max3_f32 v153, v153, v98, v99
	v_max3_f32 v0, v0, v100, v101
	v_max3_f32 v14, v14, v102, v103
	v_max3_f32 v15, v15, v104, v105
	v_max3_f32 v153, v153, v106, v107
	v_max3_f32 v0, v0, v108, v109
	v_max3_f32 v14, v14, v110, v111
	v_max3_f32 v0, v0, v15, v153
	v_max_f32_e32 v0, v0, v14
	v_mul_f32_e32 v0, 0x3e38aa3b, v0
	v_mov_b32_e32 v14, v0
	v_mov_b32_e32 v15, v0
	s_nop 1
	v_permlane32_swap_b32_e32 v14, v15
	v_max_f32_e32 v0, v14, v15
	v_add_f32_e32 v14, 0x41000000, v151
	v_cmp_gt_f32_e32 vcc, v0, v14
	s_cbranch_vccz .LBB0_344
	v_max_f32_e32 v0, v0, v0
	v_max_f32_e32 v14, v151, v151
	v_max_f32_e32 v14, v14, v0
	v_sub_f32_e32 v0, v151, v14
	v_exp_f32_e32 v0, v0
	v_mov_b32_e32 v151, v14
	v_pk_mul_f32 v[78:79], v[0:1], v[78:79] op_sel_hi:[0,1]
	v_pk_mul_f32 v[76:77], v[0:1], v[76:77] op_sel_hi:[0,1]
	v_pk_mul_f32 v[74:75], v[0:1], v[74:75] op_sel_hi:[0,1]
	v_pk_mul_f32 v[72:73], v[0:1], v[72:73] op_sel_hi:[0,1]
	v_pk_mul_f32 v[70:71], v[0:1], v[70:71] op_sel_hi:[0,1]
	v_pk_mul_f32 v[68:69], v[0:1], v[68:69] op_sel_hi:[0,1]
	v_pk_mul_f32 v[66:67], v[0:1], v[66:67] op_sel_hi:[0,1]
	v_pk_mul_f32 v[64:65], v[0:1], v[64:65] op_sel_hi:[0,1]
	v_pk_mul_f32 v[62:63], v[0:1], v[62:63] op_sel_hi:[0,1]
	v_pk_mul_f32 v[60:61], v[0:1], v[60:61] op_sel_hi:[0,1]
	v_pk_mul_f32 v[58:59], v[0:1], v[58:59] op_sel_hi:[0,1]
	v_pk_mul_f32 v[56:57], v[0:1], v[56:57] op_sel_hi:[0,1]
	v_pk_mul_f32 v[54:55], v[0:1], v[54:55] op_sel_hi:[0,1]
	v_pk_mul_f32 v[52:53], v[0:1], v[52:53] op_sel_hi:[0,1]
	v_pk_mul_f32 v[50:51], v[0:1], v[50:51] op_sel_hi:[0,1]
	v_pk_mul_f32 v[48:49], v[0:1], v[48:49] op_sel_hi:[0,1]
	v_pk_mul_f32 v[46:47], v[0:1], v[46:47] op_sel_hi:[0,1]
	v_pk_mul_f32 v[44:45], v[0:1], v[44:45] op_sel_hi:[0,1]
	v_pk_mul_f32 v[42:43], v[0:1], v[42:43] op_sel_hi:[0,1]
	v_pk_mul_f32 v[40:41], v[0:1], v[40:41] op_sel_hi:[0,1]
	v_pk_mul_f32 v[38:39], v[0:1], v[38:39] op_sel_hi:[0,1]
	v_pk_mul_f32 v[36:37], v[0:1], v[36:37] op_sel_hi:[0,1]
	v_pk_mul_f32 v[34:35], v[0:1], v[34:35] op_sel_hi:[0,1]
	v_pk_mul_f32 v[32:33], v[0:1], v[32:33] op_sel_hi:[0,1]
	v_pk_mul_f32 v[30:31], v[0:1], v[30:31] op_sel_hi:[0,1]
	v_pk_mul_f32 v[28:29], v[0:1], v[28:29] op_sel_hi:[0,1]
	v_pk_mul_f32 v[26:27], v[0:1], v[26:27] op_sel_hi:[0,1]
	v_pk_mul_f32 v[24:25], v[0:1], v[24:25] op_sel_hi:[0,1]
	v_pk_mul_f32 v[22:23], v[0:1], v[22:23] op_sel_hi:[0,1]
	v_pk_mul_f32 v[20:21], v[0:1], v[20:21] op_sel_hi:[0,1]
	v_pk_mul_f32 v[18:19], v[0:1], v[18:19] op_sel_hi:[0,1]
	v_pk_mul_f32 v[16:17], v[0:1], v[16:17] op_sel_hi:[0,1]
	v_mul_f32_e32 v150, v150, v0
	s_branch .LBB0_344

.Lc1_dmaonly:
	s_add_i32 s38, s63, 3
	s_cmp_ge_i32 s38, s53
	s_cbranch_scc1 .LBB0_345
	s_and_b32 s38, s38, 3
	s_mulk_i32 s38, 0x6000
	s_add_i32 s38, s38, 0
	v_lshl_add_u64 v[2:3], s[24:25], 0, v[148:149]
	s_add_i32 m0, s38, s59
	s_add_i32 s38, s38, s60
	global_load_lds_dwordx4 v[2:3], off
	s_add_i32 m0, s38, 0x2000
	v_lshl_add_u64 v[2:3], s[24:25], 0, v[130:131]
	global_load_lds_dwordx4 v[2:3], off
	v_lshl_add_u64 v[2:3], s[24:25], 0, v[146:147]
	s_add_i32 m0, s38, 0x2400
	s_nop 0
	global_load_lds_dwordx4 v[2:3], off
	s_branch .LBB0_345

.LBB0_362:
	v_fma_f32 v96, v96, s43, -v150
	v_exp_f32_e32 v96, v96
	v_fma_f32 v97, v97, s43, -v150
	v_exp_f32_e32 v97, v97
	v_fma_f32 v98, v98, s43, -v150
	v_exp_f32_e32 v98, v98
	v_fma_f32 v99, v99, s43, -v150
	v_exp_f32_e32 v99, v99
	v_fma_f32 v100, v100, s43, -v150
	v_exp_f32_e32 v100, v100
	v_fma_f32 v101, v101, s43, -v150
	v_exp_f32_e32 v101, v101
	v_fma_f32 v102, v102, s43, -v150
	v_exp_f32_e32 v102, v102
	v_fma_f32 v103, v103, s43, -v150
	v_exp_f32_e32 v103, v103
	v_add_f32_e32 v0, v96, v97
	v_add_f32_e32 v14, v98, v99
	v_cvt_pk_bf16_f32 v96, v96, v97
	v_cvt_pk_bf16_f32 v97, v98, v99
	v_cvt_pk_bf16_f32 v98, v100, v101
	v_cvt_pk_bf16_f32 v99, v102, v103
	v_add_f32_e32 v15, v100, v101
	v_add_f32_e32 v0, v0, v102
	v_add_f32_e32 v14, v14, v103
	s_waitcnt lgkmcnt(6)
	v_mfma_f32_32x32x16_bf16 v[16:31], v[2:5], v[96:99], v[16:31]
	ds_read_b64_tr_b16 v[156:157], v248 offset:12288
	ds_read_b64_tr_b16 v[158:159], v248 offset:14336
	ds_read_b64_tr_b16 v[160:161], v249 offset:12288
	ds_read_b64_tr_b16 v[162:163], v249 offset:14336
	ds_read_b64_tr_b16 v[252:253], v250 offset:12288
	ds_read_b64_tr_b16 v[254:255], v250 offset:14336
	ds_read_b64_tr_b16 v[100:101], v251 offset:12288
	ds_read_b64_tr_b16 v[102:103], v251 offset:14336
	v_fma_f32 v104, v104, s43, -v150
	v_exp_f32_e32 v104, v104
	v_fma_f32 v105, v105, s43, -v150
	v_exp_f32_e32 v105, v105
	s_waitcnt lgkmcnt(12)
	v_mfma_f32_32x32x16_bf16 v[32:47], v[6:9], v[96:99], v[32:47]
	v_fma_f32 v106, v106, s43, -v150
	v_exp_f32_e32 v106, v106
	v_fma_f32 v107, v107, s43, -v150
	v_exp_f32_e32 v107, v107
	s_waitcnt lgkmcnt(10)
	v_mfma_f32_32x32x16_bf16 v[48:63], v[10:13], v[96:99], v[48:63]
	v_fma_f32 v108, v108, s43, -v150
	v_exp_f32_e32 v108, v108
	v_fma_f32 v109, v109, s43, -v150
	v_exp_f32_e32 v109, v109
	s_waitcnt lgkmcnt(8)
	v_mfma_f32_32x32x16_bf16 v[64:79], v[244:247], v[96:99], v[64:79]
	v_fma_f32 v110, v110, s43, -v150
	v_exp_f32_e32 v110, v110
	v_fma_f32 v111, v111, s43, -v150
	v_exp_f32_e32 v111, v111
	v_add_f32_e32 v0, v0, v104
	v_add_f32_e32 v14, v14, v105
	v_add_f32_e32 v15, v15, v106
	v_add_f32_e32 v0, v0, v107
	v_cvt_pk_bf16_f32 v104, v104, v105
	v_cvt_pk_bf16_f32 v105, v106, v107
	v_cvt_pk_bf16_f32 v106, v108, v109
	v_cvt_pk_bf16_f32 v107, v110, v111
	v_add_f32_e32 v14, v14, v108
	v_add_f32_e32 v15, v15, v109
	v_add_f32_e32 v0, v0, v110
	v_add_f32_e32 v14, v14, v111
	s_waitcnt lgkmcnt(6)
	v_mfma_f32_32x32x16_bf16 v[16:31], v[156:159], v[104:107], v[16:31]
	ds_read_b64_tr_b16 v[2:3], v248 offset:16384
	ds_read_b64_tr_b16 v[4:5], v248 offset:18432
	ds_read_b64_tr_b16 v[6:7], v249 offset:16384
	ds_read_b64_tr_b16 v[8:9], v249 offset:18432
	ds_read_b64_tr_b16 v[10:11], v250 offset:16384
	ds_read_b64_tr_b16 v[12:13], v250 offset:18432
	ds_read_b64_tr_b16 v[244:245], v251 offset:16384
	ds_read_b64_tr_b16 v[246:247], v251 offset:18432
	v_fma_f32 v80, v80, s43, -v150
	v_exp_f32_e32 v80, v80
	v_fma_f32 v81, v81, s43, -v150
	v_exp_f32_e32 v81, v81
	s_waitcnt lgkmcnt(12)
	v_mfma_f32_32x32x16_bf16 v[32:47], v[160:163], v[104:107], v[32:47]
	v_fma_f32 v82, v82, s43, -v150
	v_exp_f32_e32 v82, v82
	v_fma_f32 v83, v83, s43, -v150
	v_exp_f32_e32 v83, v83
	s_waitcnt lgkmcnt(10)
	v_mfma_f32_32x32x16_bf16 v[48:63], v[252:255], v[104:107], v[48:63]
	v_fma_f32 v84, v84, s43, -v150
	v_exp_f32_e32 v84, v84
	v_fma_f32 v85, v85, s43, -v150
	v_exp_f32_e32 v85, v85
	s_waitcnt lgkmcnt(8)
	v_mfma_f32_32x32x16_bf16 v[64:79], v[100:103], v[104:107], v[64:79]
	v_fma_f32 v86, v86, s43, -v150
	v_exp_f32_e32 v86, v86
	v_fma_f32 v87, v87, s43, -v150
	v_exp_f32_e32 v87, v87
	v_add_f32_e32 v0, v0, v80
	v_add_f32_e32 v14, v14, v81
	v_add_f32_e32 v15, v15, v82
	v_add_f32_e32 v0, v0, v83
	v_cvt_pk_bf16_f32 v80, v80, v81
	v_cvt_pk_bf16_f32 v81, v82, v83
	v_cvt_pk_bf16_f32 v82, v84, v85
	v_cvt_pk_bf16_f32 v83, v86, v87
	v_add_f32_e32 v14, v14, v84
	v_add_f32_e32 v15, v15, v85
	v_add_f32_e32 v0, v0, v86
	v_add_f32_e32 v14, v14, v87
	s_waitcnt lgkmcnt(6)
	v_mfma_f32_32x32x16_bf16 v[16:31], v[2:5], v[80:83], v[16:31]
	ds_read_b64_tr_b16 v[156:157], v248 offset:20480
	ds_read_b64_tr_b16 v[158:159], v248 offset:22528
	ds_read_b64_tr_b16 v[160:161], v249 offset:20480
	ds_read_b64_tr_b16 v[162:163], v249 offset:22528
	ds_read_b64_tr_b16 v[252:253], v250 offset:20480
	ds_read_b64_tr_b16 v[254:255], v250 offset:22528
	ds_read_b64_tr_b16 v[100:101], v251 offset:20480
	ds_read_b64_tr_b16 v[102:103], v251 offset:22528
	v_fma_f32 v88, v88, s43, -v150
	v_exp_f32_e32 v88, v88
	v_fma_f32 v89, v89, s43, -v150
	v_exp_f32_e32 v89, v89
	s_waitcnt lgkmcnt(12)
	v_mfma_f32_32x32x16_bf16 v[32:47], v[6:9], v[80:83], v[32:47]
	v_fma_f32 v90, v90, s43, -v150
	v_exp_f32_e32 v90, v90
	v_fma_f32 v91, v91, s43, -v150
	v_exp_f32_e32 v91, v91
	s_waitcnt lgkmcnt(10)
	v_mfma_f32_32x32x16_bf16 v[48:63], v[10:13], v[80:83], v[48:63]
	v_fma_f32 v92, v92, s43, -v150
	v_exp_f32_e32 v92, v92
	v_fma_f32 v93, v93, s43, -v150
	v_exp_f32_e32 v93, v93
	s_waitcnt lgkmcnt(8)
	v_mfma_f32_32x32x16_bf16 v[64:79], v[244:247], v[80:83], v[64:79]
	v_fma_f32 v94, v94, s43, -v150
	v_exp_f32_e32 v94, v94
	v_fma_f32 v95, v95, s43, -v150
	v_exp_f32_e32 v95, v95
	v_add_f32_e32 v0, v0, v88
	v_add_f32_e32 v14, v14, v89
	v_add_f32_e32 v15, v15, v90
	v_add_f32_e32 v0, v0, v91
	v_cvt_pk_bf16_f32 v88, v88, v89
	v_cvt_pk_bf16_f32 v89, v90, v91
	v_cvt_pk_bf16_f32 v90, v92, v93
	v_cvt_pk_bf16_f32 v91, v94, v95
	v_add_f32_e32 v14, v14, v92
	v_add_f32_e32 v15, v15, v93
	v_add_f32_e32 v0, v0, v94
	v_add_f32_e32 v14, v14, v95
	s_waitcnt lgkmcnt(6)
	v_mfma_f32_32x32x16_bf16 v[16:31], v[156:159], v[88:91], v[16:31]
	s_waitcnt lgkmcnt(4)
	v_mfma_f32_32x32x16_bf16 v[32:47], v[160:163], v[88:91], v[32:47]
	s_waitcnt lgkmcnt(2)
	v_mfma_f32_32x32x16_bf16 v[48:63], v[252:255], v[88:91], v[48:63]
	s_waitcnt lgkmcnt(0)
	v_mfma_f32_32x32x16_bf16 v[64:79], v[100:103], v[88:91], v[64:79]
	v_add_f32_e32 v0, v0, v14
	v_add_f32_e32 v154, v154, v15
	v_add_f32_e32 v154, v154, v0

.LBB0_371:
	s_waitcnt lgkmcnt(0)
	s_barrier
	s_cmp_gt_i32 s34, s52
	s_cbranch_scc1 .Lc2_dmaonly
	s_and_b32 s28, s34, 3
	s_mulk_i32 s28, 0x6000
	s_add_i32 s28, s28, 0
	v_add_u32_e32 v0, s28, v174
	v_add_u32_e32 v14, v0, v173
	v_add_u32_e32 v15, v0, v177
	ds_read_b128 v[2:5], v14
	ds_read_b128 v[6:9], v14 offset:4096
	ds_read_b128 v[10:13], v15
	ds_read_b128 v[252:255], v15 offset:4096
	v_add_u32_e32 v14, v0, v179
	v_add_u32_e32 v15, v0, v180
	ds_read_b128 v[156:159], v14
	ds_read_b128 v[160:163], v14 offset:4096
	ds_read_b128 v[244:247], v15
	ds_read_b128 v[248:251], v15 offset:4096
	s_add_i32 s101, s34, 3
	s_cmp_ge_i32 s101, s53
	s_cbranch_scc1 .Lc2_go
	s_and_b32 s101, s101, 3
	s_mulk_i32 s101, 0x6000
	s_add_i32 s101, s101, 0
	v_lshl_add_u64 v[14:15], s[26:27], 0, v[148:149]
	s_add_i32 m0, s101, s4
	s_add_i32 s101, s101, s36
	global_load_lds_dwordx4 v[14:15], off
	s_add_i32 m0, s101, 0x2000
	v_lshl_add_u64 v[14:15], s[26:27], 0, v[128:129]
	global_load_lds_dwordx4 v[14:15], off
	v_lshl_add_u64 v[14:15], s[26:27], 0, v[130:131]
	s_add_i32 m0, s101, 0x2400
	s_nop 0
	global_load_lds_dwordx4 v[14:15], off
.Lc2_go:
	s_waitcnt lgkmcnt(6)
	v_mfma_f32_32x32x16_bf16 v[96:111], v[2:5], v[112:115], 0
	v_mfma_f32_32x32x16_bf16 v[80:95], v[6:9], v[112:115], 0
	s_waitcnt lgkmcnt(4)
	v_mfma_f32_32x32x16_bf16 v[96:111], v[10:13], v[116:119], v[96:111]
	v_mfma_f32_32x32x16_bf16 v[80:95], v[252:255], v[116:119], v[80:95]
	s_waitcnt lgkmcnt(2)
	v_mfma_f32_32x32x16_bf16 v[96:111], v[156:159], v[120:123], v[96:111]
	v_mfma_f32_32x32x16_bf16 v[80:95], v[160:163], v[120:123], v[80:95]
	s_waitcnt lgkmcnt(0)
	v_mfma_f32_32x32x16_bf16 v[80:95], v[248:251], v[124:127], v[80:95]
	v_mfma_f32_32x32x16_bf16 v[96:111], v[244:247], v[124:127], v[96:111]
	v_add3_u32 v14, s28, v185, v186
	v_add3_u32 v14, v14, v175, v176
	v_add_u32_e32 v248, v14, v187
	v_add_u32_e32 v249, v14, v190
	v_add_u32_e32 v250, v14, v191
	v_add_u32_e32 v251, v14, v192
	ds_read_b64_tr_b16 v[2:3], v248 offset:8192
	ds_read_b64_tr_b16 v[4:5], v248 offset:10240
	ds_read_b64_tr_b16 v[6:7], v249 offset:8192
	ds_read_b64_tr_b16 v[8:9], v249 offset:10240
	ds_read_b64_tr_b16 v[10:11], v250 offset:8192
	ds_read_b64_tr_b16 v[12:13], v250 offset:10240
	ds_read_b64_tr_b16 v[244:245], v251 offset:8192
	ds_read_b64_tr_b16 v[246:247], v251 offset:10240
	v_max3_f32 v0, v80, v81, v82
	v_max3_f32 v14, v83, v84, v85
	v_max3_f32 v15, v86, v87, v88
	v_max3_f32 v153, v89, v90, v91
	v_max3_f32 v0, v0, v92, v93
	v_max3_f32 v14, v14, v94, v95
	v_max3_f32 v15, v15, v96, v97
	v_max3_f32 v153, v153, v98, v99
	v_max3_f32 v0, v0, v100, v101
	v_max3_f32 v14, v14, v102, v103
	v_max3_f32 v15, v15, v104, v105
	v_max3_f32 v153, v153, v106, v107
	v_max3_f32 v0, v0, v108, v109
	v_max3_f32 v14, v14, v110, v111
	v_max3_f32 v0, v0, v15, v153
	v_max_f32_e32 v0, v0, v14
	v_mul_f32_e32 v0, 0x3e38aa3b, v0
	v_mov_b32_e32 v14, v0
	v_mov_b32_e32 v15, v0
	s_nop 1
	v_permlane32_swap_b32_e32 v14, v15
	v_max_f32_e32 v0, v14, v15
	v_add_f32_e32 v14, 0x41000000, v150
	v_cmp_gt_f32_e32 vcc, v0, v14
	s_cbranch_vccz .LBB0_362
	v_max_f32_e32 v0, v0, v0
	v_max_f32_e32 v14, v150, v150
	v_max_f32_e32 v14, v14, v0
	v_sub_f32_e32 v0, v150, v14
	v_exp_f32_e32 v0, v0
	v_mov_b32_e32 v150, v14
	v_pk_mul_f32 v[30:31], v[30:31], v[0:1] op_sel_hi:[1,0]
	v_pk_mul_f32 v[28:29], v[28:29], v[0:1] op_sel_hi:[1,0]
	v_pk_mul_f32 v[26:27], v[26:27], v[0:1] op_sel_hi:[1,0]
	v_pk_mul_f32 v[24:25], v[24:25], v[0:1] op_sel_hi:[1,0]
	v_pk_mul_f32 v[22:23], v[22:23], v[0:1] op_sel_hi:[1,0]
	v_pk_mul_f32 v[20:21], v[20:21], v[0:1] op_sel_hi:[1,0]
	v_pk_mul_f32 v[18:19], v[18:19], v[0:1] op_sel_hi:[1,0]
	v_pk_mul_f32 v[16:17], v[16:17], v[0:1] op_sel_hi:[1,0]
	v_pk_mul_f32 v[46:47], v[46:47], v[0:1] op_sel_hi:[1,0]
	v_pk_mul_f32 v[44:45], v[44:45], v[0:1] op_sel_hi:[1,0]
	v_pk_mul_f32 v[42:43], v[42:43], v[0:1] op_sel_hi:[1,0]
	v_pk_mul_f32 v[40:41], v[40:41], v[0:1] op_sel_hi:[1,0]
	v_pk_mul_f32 v[38:39], v[38:39], v[0:1] op_sel_hi:[1,0]
	v_pk_mul_f32 v[36:37], v[36:37], v[0:1] op_sel_hi:[1,0]
	v_pk_mul_f32 v[34:35], v[34:35], v[0:1] op_sel_hi:[1,0]
	v_pk_mul_f32 v[32:33], v[32:33], v[0:1] op_sel_hi:[1,0]
	v_pk_mul_f32 v[62:63], v[62:63], v[0:1] op_sel_hi:[1,0]
	v_pk_mul_f32 v[60:61], v[60:61], v[0:1] op_sel_hi:[1,0]
	v_pk_mul_f32 v[58:59], v[58:59], v[0:1] op_sel_hi:[1,0]
	v_pk_mul_f32 v[56:57], v[56:57], v[0:1] op_sel_hi:[1,0]
	v_pk_mul_f32 v[54:55], v[54:55], v[0:1] op_sel_hi:[1,0]
	v_pk_mul_f32 v[52:53], v[52:53], v[0:1] op_sel_hi:[1,0]
	v_pk_mul_f32 v[50:51], v[50:51], v[0:1] op_sel_hi:[1,0]
	v_pk_mul_f32 v[48:49], v[48:49], v[0:1] op_sel_hi:[1,0]
	v_pk_mul_f32 v[78:79], v[78:79], v[0:1] op_sel_hi:[1,0]
	v_pk_mul_f32 v[76:77], v[76:77], v[0:1] op_sel_hi:[1,0]
	v_pk_mul_f32 v[74:75], v[74:75], v[0:1] op_sel_hi:[1,0]
	v_pk_mul_f32 v[72:73], v[72:73], v[0:1] op_sel_hi:[1,0]
	v_pk_mul_f32 v[70:71], v[70:71], v[0:1] op_sel_hi:[1,0]
	v_pk_mul_f32 v[68:69], v[68:69], v[0:1] op_sel_hi:[1,0]
	v_pk_mul_f32 v[66:67], v[66:67], v[0:1] op_sel_hi:[1,0]
	v_pk_mul_f32 v[64:65], v[64:65], v[0:1] op_sel_hi:[1,0]
	v_mul_f32_e32 v154, v154, v0
	s_branch .LBB0_362

.Lc2_dmaonly:
	s_add_i32 s28, s34, 3
	s_cmp_ge_i32 s28, s53
	s_cbranch_scc1 .LBB0_363
	s_and_b32 s28, s28, 3
	s_mulk_i32 s28, 0x6000
	s_add_i32 s28, s28, 0
	v_lshl_add_u64 v[2:3], s[26:27], 0, v[148:149]
	s_add_i32 m0, s28, s4
	s_add_i32 s28, s28, s36
	global_load_lds_dwordx4 v[2:3], off
	s_add_i32 m0, s28, 0x2000
	v_lshl_add_u64 v[2:3], s[26:27], 0, v[128:129]
	global_load_lds_dwordx4 v[2:3], off
	v_lshl_add_u64 v[2:3], s[26:27], 0, v[130:131]
	s_add_i32 m0, s28, 0x2400
	s_nop 0
	global_load_lds_dwordx4 v[2:3], off
	s_branch .LBB0_363

	.amdhsa_kernel _Z6mk_fwd4Args
		.amdhsa_group_segment_fixed_size 0
		.amdhsa_private_segment_fixed_size 0
		.amdhsa_kernarg_size 456
		.amdhsa_user_sgpr_count 2
		.amdhsa_user_sgpr_dispatch_ptr 0
		.amdhsa_user_sgpr_queue_ptr 0
		.amdhsa_user_sgpr_kernarg_segment_ptr 1
		.amdhsa_user_sgpr_dispatch_id 0
		.amdhsa_user_sgpr_kernarg_preload_length 0
		.amdhsa_user_sgpr_kernarg_preload_offset 0
		.amdhsa_user_sgpr_private_segment_size 0
		.amdhsa_uses_dynamic_stack 0
		.amdhsa_enable_private_segment 0
		.amdhsa_system_sgpr_workgroup_id_x 1
		.amdhsa_system_sgpr_workgroup_id_y 0
		.amdhsa_system_sgpr_workgroup_id_z 0
		.amdhsa_system_sgpr_workgroup_info 0
		.amdhsa_system_vgpr_workitem_id 2
		.amdhsa_next_free_vgpr 256
		.amdhsa_next_free_sgpr 102
		.amdhsa_accum_offset 256
		.amdhsa_reserve_vcc 1
		.amdhsa_float_round_mode_32 0
		.amdhsa_float_round_mode_16_64 0
		.amdhsa_float_denorm_mode_32 3
		.amdhsa_float_denorm_mode_16_64 3
		.amdhsa_dx10_clamp 1
		.amdhsa_ieee_mode 1
		.amdhsa_fp16_overflow 0
		.amdhsa_tg_split 0
		.amdhsa_exception_fp_ieee_invalid_op 0
		.amdhsa_exception_fp_denorm_src 0
		.amdhsa_exception_fp_ieee_div_zero 0
		.amdhsa_exception_fp_ieee_overflow 0
		.amdhsa_exception_fp_ieee_underflow 0
		.amdhsa_exception_fp_ieee_inexact 0
		.amdhsa_exception_int_div_zero 0
	.end_amdhsa_kernel

amdhsa.kernels:
  - .agpr_count:     0
    .args:
      - .offset:         0
        .size:           200
        .value_kind:     by_value
      - .offset:         200
        .size:           4
        .value_kind:     hidden_block_count_x
      - .offset:         204
        .size:           4
        .value_kind:     hidden_block_count_y
      - .offset:         208
        .size:           4
        .value_kind:     hidden_block_count_z
      - .offset:         212
        .size:           2
        .value_kind:     hidden_group_size_x
      - .offset:         214
        .size:           2
        .value_kind:     hidden_group_size_y
      - .offset:         216
        .size:           2
        .value_kind:     hidden_group_size_z
      - .offset:         218
        .size:           2
        .value_kind:     hidden_remainder_x
      - .offset:         220
        .size:           2
        .value_kind:     hidden_remainder_y
      - .offset:         222
        .size:           2
        .value_kind:     hidden_remainder_z
      - .offset:         240
        .size:           8
        .value_kind:     hidden_global_offset_x
      - .offset:         248
        .size:           8
        .value_kind:     hidden_global_offset_y
      - .offset:         256
        .size:           8
        .value_kind:     hidden_global_offset_z
      - .offset:         264
        .size:           2
        .value_kind:     hidden_grid_dims
      - .offset:         288
        .size:           8
        .value_kind:     hidden_multigrid_sync_arg
      - .offset:         320
        .size:           4
        .value_kind:     hidden_dynamic_lds_size
    .group_segment_fixed_size: 0
    .kernarg_segment_align: 8
    .kernarg_segment_size: 456
    .language:       OpenCL C
    .language_version:
      - 2
      - 0
    .max_flat_workgroup_size: 512
    .name:           _Z6mk_fwd4Args
    .private_segment_fixed_size: 0
    .sgpr_count:     108
    .sgpr_spill_count: 69
    .symbol:         _Z6mk_fwd4Args.kd
    .uniform_work_group_size: 1
    .uses_dynamic_stack: false
    .vgpr_count:     256
    .vgpr_spill_count: 0
    .wavefront_size: 64
